# L3 K-norm+rope phase de-serialised too (gains hoisted, rope in two batched groups, branch-free)
# baseline (speedup 1.0000x reference)
; #define OPAQUE_IDS int tx = threadIdx.x; int bx = blockIdx.x; asm volatile("" : "+v"(tx), "+s"(bx));
; template <int HS>
; DI void qknorm_phase(bf16_t* QK, int RL, const float* kgain, int gain_mod, const f32x2* rope) {
;     OPAQUE_IDS
;     const int lane = tx & 63, gw = bx * 8 + (tx >> 6), nw = gridDim.x * 8;
;     const int lpr = (RL - 1024) / HS, rpw = 64 / lpr, rsub = lane / lpr, kl = lane - rsub * lpr, seg = kl >> 1, half = kl & 1;
;     const float* gn = kgain + (gain_mod ? (seg % gain_mod) * 2 * HS : 0) + half * HS;
;     for (int row0 = gw * rpw; row0 < T; row0 += nw * rpw) {
;         const int row = row0 + rsub; const bool act = row < T; const int rowc = act ? row : T - 1;
;         const int b = rowc / LT, pos = rowc - b * LT;
;         float x[HS]; float ss = 0.f;
;         bf16_t* ptr = QK + (size_t)rowc * RL + 1024 + kl * HS;
.LBB0_3202:
	s_or_b64 exec, exec, s[0:1]
	s_mov_b32 s0, s87
	s_waitcnt lgkmcnt(0)
	v_mov_b32_e32 v0, v252
	s_barrier
	s_add_u32 s8, s68, 0x958000
	v_ashrrev_i32_e32 v1, 2, v0
	v_and_b32_e32 v1, -16, v1
	v_lshl_add_u32 v20, s0, 7, v1
	s_movk_i32 s14, 0x4800
	s_addc_u32 s9, s69, 0
	v_cmp_gt_i32_e32 vcc, s14, v20
	s_and_saveexec_b64 s[10:11], vcc
	s_cbranch_execz .LBB0_3335
	v_and_b32_e32 v1, 1, v0
	v_readlane_b32 s36, v254, 23
	v_bfe_u32 v21, v0, 2, 4
	v_lshlrev_b32_e32 v4, 8, v1
	v_mov_b32_e32 v5, 0
	v_readlane_b32 s50, v254, 37
	v_readlane_b32 s51, v254, 38
	v_lshlrev_b32_e32 v0, 7, v0
	v_cmp_eq_u32_e32 vcc, 0, v1
	v_lshl_add_u64 v[6:7], s[50:51], 0, v[4:5]
	v_and_b32_e32 v4, 0x180, v0
	s_lshl_b32 s15, s26, 7
	v_lshl_add_u64 v[8:9], s[96:97], 0, v[4:5]
	s_mov_b64 s[12:13], 0
	s_movk_i32 s24, 0x47ff
	v_mov_b32_e32 v22, 0x47ff
	s_movk_i32 s25, 0xa00
	s_mov_b32 s30, 0x38e38e39
	v_mov_b32_e32 v23, 0x358637bd
	s_mov_b32 s31, 0x800000
	s_movk_i32 s34, 0xff
	v_readlane_b32 s37, v254, 24
	v_readlane_b32 s38, v254, 25
	v_readlane_b32 s39, v254, 26
	v_readlane_b32 s40, v254, 27
	v_readlane_b32 s41, v254, 28
	v_readlane_b32 s42, v254, 29
	v_readlane_b32 s43, v254, 30
	v_readlane_b32 s44, v254, 31
	v_readlane_b32 s45, v254, 32
	v_readlane_b32 s46, v254, 33
	v_readlane_b32 s47, v254, 34
	v_readlane_b32 s48, v254, 35
	v_readlane_b32 s49, v254, 36
	global_load_dwordx4 v[96:99], v[6:7], off
	global_load_dwordx4 v[100:103], v[6:7], off offset:16
	global_load_dwordx4 v[104:107], v[6:7], off offset:32
	global_load_dwordx4 v[108:111], v[6:7], off offset:48
	global_load_dwordx4 v[112:115], v[6:7], off offset:64
	global_load_dwordx4 v[116:119], v[6:7], off offset:80
	global_load_dwordx4 v[120:123], v[6:7], off offset:96
	global_load_dwordx4 v[124:127], v[6:7], off offset:112
	global_load_dwordx4 v[128:131], v[6:7], off offset:128
	global_load_dwordx4 v[132:135], v[6:7], off offset:144
	global_load_dwordx4 v[136:139], v[6:7], off offset:160
	global_load_dwordx4 v[144:147], v[6:7], off offset:176
	global_load_dwordx4 v[148:151], v[6:7], off offset:192
	global_load_dwordx4 v[152:155], v[6:7], off offset:208
	global_load_dwordx4 v[156:159], v[6:7], off offset:224
	global_load_dwordx4 v[160:163], v[6:7], off offset:240
	s_branch .LBB0_3205

; DI float bflo(unsigned w) { return __uint_as_float(w << 16); }
; DI float bfhi(unsigned w) { return __uint_as_float(w & 0xffff0000u); }
; template <int CTRL> DI float dpp_f(float x) { return __int_as_float(__builtin_amdgcn_update_dpp(0, __float_as_int(x), CTRL, 0xF, 0xF, true)); }
; template <int HS>
; DI void qknorm_phase(bf16_t* QK, int RL, const float* kgain, int gain_mod, const f32x2* rope) {
;     ...
;     for (int row0 = gw * rpw; row0 < T; row0 += nw * rpw) {
;         const int row = row0 + rsub; const bool act = row < T; const int rowc = act ? row : T - 1;
;         const int b = rowc / LT, pos = rowc - b * LT;
;         float x[HS]; float ss = 0.f;
;         bf16_t* ptr = QK + (size_t)rowc * RL + 1024 + kl * HS;
; #pragma unroll
;         for (int c = 0; c < HS / 8; ++c) { const u32x4 w = *(const u32x4*)(ptr + c * 8);
;             x[c * 8 + 0] = bflo(w.x); x[c * 8 + 1] = bfhi(w.x); x[c * 8 + 2] = bflo(w.y); x[c * 8 + 3] = bfhi(w.y);
;             x[c * 8 + 4] = bflo(w.z); x[c * 8 + 5] = bfhi(w.z); x[c * 8 + 6] = bflo(w.w); x[c * 8 + 7] = bfhi(w.w); }
; #pragma unroll
;         for (int e = 0; e < HS; ++e) ss += x[e] * x[e];
;         ss += dpp_f<0xB1>(ss);
;         const float r = rsqrtf(ss * (1.f / (2 * HS)) + EPS);
;         const bool lat = pos >= LC; const f32x2* rp = rope + (size_t)(lat ? pos - LC : 0) * HS;
.LBB0_3205:
	v_add_u32_e32 v0, v21, v20
	v_cmp_gt_i32_e64 s[2:3], s14, v0
	s_nop 1
	v_cndmask_b32_e64 v4, v22, v0, s[2:3]
	v_mad_i64_i32 v[10:11], s[0:1], v4, s25, v[8:9]
	global_load_dwordx4 v[12:15], v[10:11], off offset:2048
	global_load_dwordx4 v[16:19], v[10:11], off offset:2064
	global_load_dwordx4 v[58:61], v[10:11], off offset:2080
	global_load_dwordx4 v[0:3], v[10:11], off offset:2096
	global_load_dwordx4 v[78:81], v[10:11], off offset:2112
	global_load_dwordx4 v[82:85], v[10:11], off offset:2128
	global_load_dwordx4 v[86:89], v[10:11], off offset:2144
	global_load_dwordx4 v[90:93], v[10:11], off offset:2160
	v_mul_hi_i32 v228, v4, s30
	v_lshrrev_b32_e32 v229, 31, v228
	v_ashrrev_i32_e32 v228, 9, v228
	v_add_u32_e32 v228, v228, v229
	v_mul_i32_i24_e32 v228, 0x900, v228
	v_sub_u32_e32 v228, v4, v228
	v_max_i32_e32 v228, 0x100, v228
	v_add_u32_e32 v228, 0xffffff00, v228
	v_mov_b32_e32 v229, 0
	v_lshlrev_b64 v[228:229], 9, v[228:229]
	v_lshl_add_u64 v[228:229], s[8:9], 0, v[228:229]
	global_load_dwordx4 v[164:167], v[228:229], off
	global_load_dwordx4 v[168:171], v[228:229], off offset:16
	global_load_dwordx4 v[172:175], v[228:229], off offset:32
	global_load_dwordx4 v[176:179], v[228:229], off offset:48
	global_load_dwordx4 v[180:183], v[228:229], off offset:64
	global_load_dwordx4 v[184:187], v[228:229], off offset:80
	global_load_dwordx4 v[188:191], v[228:229], off offset:96
	global_load_dwordx4 v[192:195], v[228:229], off offset:112
	global_load_dwordx4 v[196:199], v[228:229], off offset:128
	global_load_dwordx4 v[200:203], v[228:229], off offset:144
	global_load_dwordx4 v[204:207], v[228:229], off offset:160
	global_load_dwordx4 v[208:211], v[228:229], off offset:176
	global_load_dwordx4 v[212:215], v[228:229], off offset:192
	global_load_dwordx4 v[216:219], v[228:229], off offset:208
	global_load_dwordx4 v[220:223], v[228:229], off offset:224
	global_load_dwordx4 v[224:227], v[228:229], off offset:240
	v_mul_hi_i32 v24, v4, s30
	s_waitcnt vmcnt(23)
	v_and_b32_e32 v25, 0xffff0000, v12
	v_lshlrev_b32_e32 v95, 16, v12
	v_lshlrev_b32_e32 v26, 16, v13
	v_and_b32_e32 v27, 0xffff0000, v13
	v_lshlrev_b32_e32 v28, 16, v14
	v_and_b32_e32 v29, 0xffff0000, v14
	s_waitcnt vmcnt(17)
	v_lshlrev_b32_e32 v41, 16, v86
	v_and_b32_e32 v39, 0xffff0000, v86
	v_mul_f32_e32 v86, v25, v25
	v_fmac_f32_e32 v86, v95, v95
	v_fmac_f32_e32 v86, v26, v26
	v_fmac_f32_e32 v86, v27, v27
	v_fmac_f32_e32 v86, v28, v28
	v_lshlrev_b32_e32 v30, 16, v15
	v_fmac_f32_e32 v86, v29, v29
	v_and_b32_e32 v32, 0xffff0000, v15
	v_fmac_f32_e32 v86, v30, v30
	v_lshlrev_b32_e32 v34, 16, v16
	v_fmac_f32_e32 v86, v32, v32
	v_and_b32_e32 v36, 0xffff0000, v16
	v_fmac_f32_e32 v86, v34, v34
	v_lshlrev_b32_e32 v38, 16, v17
	v_fmac_f32_e32 v86, v36, v36
	v_and_b32_e32 v40, 0xffff0000, v17
	v_fmac_f32_e32 v86, v38, v38
	v_lshlrev_b32_e32 v42, 16, v18
	v_fmac_f32_e32 v86, v40, v40
	v_and_b32_e32 v44, 0xffff0000, v18
	v_fmac_f32_e32 v86, v42, v42
	v_lshlrev_b32_e32 v46, 16, v19
	v_fmac_f32_e32 v86, v44, v44
	v_and_b32_e32 v48, 0xffff0000, v19
	v_fmac_f32_e32 v86, v46, v46
	v_lshlrev_b32_e32 v50, 16, v58
	v_fmac_f32_e32 v86, v48, v48
	v_and_b32_e32 v52, 0xffff0000, v58
	v_fmac_f32_e32 v86, v50, v50
	v_lshlrev_b32_e32 v54, 16, v59
	v_fmac_f32_e32 v86, v52, v52
	v_and_b32_e32 v56, 0xffff0000, v59
	v_fmac_f32_e32 v86, v54, v54
	v_lshlrev_b32_e32 v58, 16, v60
	v_fmac_f32_e32 v86, v56, v56
	v_and_b32_e32 v60, 0xffff0000, v60
	v_fmac_f32_e32 v86, v58, v58
	v_lshlrev_b32_e32 v62, 16, v61
	v_fmac_f32_e32 v86, v60, v60
	v_and_b32_e32 v64, 0xffff0000, v61
	v_fmac_f32_e32 v86, v62, v62
	v_lshlrev_b32_e32 v66, 16, v0
	v_fmac_f32_e32 v86, v64, v64
	v_and_b32_e32 v68, 0xffff0000, v0
	v_fmac_f32_e32 v86, v66, v66
	v_lshlrev_b32_e32 v70, 16, v1
	v_fmac_f32_e32 v86, v68, v68
	v_and_b32_e32 v72, 0xffff0000, v1
	v_fmac_f32_e32 v86, v70, v70
	v_lshlrev_b32_e32 v74, 16, v2
	v_fmac_f32_e32 v86, v72, v72
	v_and_b32_e32 v76, 0xffff0000, v2
	v_fmac_f32_e32 v86, v74, v74
	v_lshlrev_b32_e32 v77, 16, v3
	v_fmac_f32_e32 v86, v76, v76
	v_and_b32_e32 v75, 0xffff0000, v3
	v_fmac_f32_e32 v86, v77, v77
	v_lshlrev_b32_e32 v73, 16, v78
	v_fmac_f32_e32 v86, v75, v75
	v_and_b32_e32 v71, 0xffff0000, v78
	v_fmac_f32_e32 v86, v73, v73
	v_lshlrev_b32_e32 v69, 16, v79
	v_fmac_f32_e32 v86, v71, v71
	v_and_b32_e32 v67, 0xffff0000, v79
	v_fmac_f32_e32 v86, v69, v69
	v_lshlrev_b32_e32 v65, 16, v80
	v_fmac_f32_e32 v86, v67, v67
	v_and_b32_e32 v63, 0xffff0000, v80
	v_fmac_f32_e32 v86, v65, v65
	v_lshlrev_b32_e32 v61, 16, v81
	v_fmac_f32_e32 v86, v63, v63
	v_and_b32_e32 v59, 0xffff0000, v81
	v_fmac_f32_e32 v86, v61, v61
	v_lshlrev_b32_e32 v57, 16, v82
	v_fmac_f32_e32 v86, v59, v59
	v_and_b32_e32 v55, 0xffff0000, v82
	v_fmac_f32_e32 v86, v57, v57
	v_lshlrev_b32_e32 v53, 16, v83
	v_fmac_f32_e32 v86, v55, v55
	v_and_b32_e32 v51, 0xffff0000, v83
	v_fmac_f32_e32 v86, v53, v53
	v_lshlrev_b32_e32 v49, 16, v84
	v_fmac_f32_e32 v86, v51, v51
	v_and_b32_e32 v47, 0xffff0000, v84
	v_fmac_f32_e32 v86, v49, v49
	v_lshlrev_b32_e32 v45, 16, v85
	v_fmac_f32_e32 v86, v47, v47
	v_and_b32_e32 v43, 0xffff0000, v85
	v_fmac_f32_e32 v86, v45, v45
	v_fmac_f32_e32 v86, v43, v43
	v_fmac_f32_e32 v86, v41, v41
	v_lshlrev_b32_e32 v37, 16, v87
	v_fmac_f32_e32 v86, v39, v39
	v_and_b32_e32 v35, 0xffff0000, v87
	v_fmac_f32_e32 v86, v37, v37
	v_lshlrev_b32_e32 v33, 16, v88
	v_fmac_f32_e32 v86, v35, v35
	v_and_b32_e32 v31, 0xffff0000, v88
	v_and_b32_e32 v18, 0xffff0000, v89
	v_lshlrev_b32_e32 v19, 16, v89
	v_fmac_f32_e32 v86, v33, v33
	v_pk_mul_f32 v[12:13], v[18:19], v[18:19]
	v_fmac_f32_e32 v86, v31, v31
	s_waitcnt vmcnt(16)
; template <int CTRL> DI float dpp_f(float x) { return __int_as_float(__builtin_amdgcn_update_dpp(0, __float_as_int(x), CTRL, 0xF, 0xF, true)); }
; template <int HS>
; DI void qknorm_phase(bf16_t* QK, int RL, const float* kgain, int gain_mod, const f32x2* rope) {
;     ...
; #pragma unroll
;         for (int e = 0; e < HS; ++e) ss += x[e] * x[e];
;         ss += dpp_f<0xB1>(ss);
;         const float r = rsqrtf(ss * (1.f / (2 * HS)) + EPS);
;         const bool lat = pos >= LC; const f32x2* rp = rope + (size_t)(lat ? pos - LC : 0) * HS;
; #pragma unroll
;         for (int e = 0; e < HS; ++e) {
;             float v = x[e] * r * gn[e];
;             const float o = dpp_f<0xB1>(v);
	v_and_b32_e32 v16, 0xffff0000, v90
	v_lshlrev_b32_e32 v17, 16, v90
	v_add_f32_e32 v13, v13, v86
	v_pk_mul_f32 v[78:79], v[16:17], v[16:17]
	v_add_f32_e32 v12, v12, v13
	v_and_b32_e32 v14, 0xffff0000, v91
	v_lshlrev_b32_e32 v15, 16, v91
	v_add_f32_e32 v12, v79, v12
	v_pk_mul_f32 v[80:81], v[14:15], v[14:15]
	v_add_f32_e32 v12, v78, v12
	v_and_b32_e32 v2, 0xffff0000, v92
	v_lshlrev_b32_e32 v3, 16, v92
	v_add_f32_e32 v12, v81, v12
	v_pk_mul_f32 v[82:83], v[2:3], v[2:3]
	v_add_f32_e32 v12, v80, v12
	v_and_b32_e32 v0, 0xffff0000, v93
	v_lshlrev_b32_e32 v1, 16, v93
	v_add_f32_e32 v12, v83, v12
	v_pk_mul_f32 v[84:85], v[0:1], v[0:1]
	v_add_f32_e32 v12, v82, v12
	v_add_f32_e32 v12, v85, v12
	v_add_f32_e32 v12, v84, v12
	v_lshrrev_b32_e32 v13, 31, v24
	v_ashrrev_i32_e32 v24, 9, v24
	v_add_f32_dpp v12, v12, v12 quad_perm:[1,0,3,2] row_mask:0xf bank_mask:0xf bound_ctrl:1
	v_fmamk_f32 v12, v12, 0x3c000000, v23
	v_mul_f32_e32 v78, 0x4b800000, v12
	v_cmp_gt_f32_e64 s[0:1], s31, v12
	v_add_u32_e32 v13, v24, v13
	v_mul_i32_i24_e32 v13, 0x900, v13
	v_cndmask_b32_e64 v12, v12, v78, s[0:1]
	v_rsq_f32_e32 v12, v12
	v_sub_u32_e32 v4, v4, v13
	v_cmp_lt_i32_e64 s[4:5], s34, v4
	v_max_i32_e32 v4, 0x100, v4
	v_mul_f32_e32 v13, 0x45800000, v12
	v_cndmask_b32_e64 v24, v12, v13, s[0:1]
	v_add_u32_e32 v4, 0xffffff00, v4
	v_lshlrev_b64 v[12:13], 9, v[4:5]
	v_mul_f32_e32 v4, v24, v95
	v_mul_f32_e32 v25, v24, v25
	v_mul_f32_e32 v26, v24, v26
	v_mul_f32_e32 v27, v24, v27
	v_mul_f32_e32 v28, v24, v28
	v_mul_f32_e32 v29, v24, v29
	v_mul_f32_e32 v30, v24, v30
	v_mul_f32_e32 v32, v24, v32
	v_mul_f32_e32 v34, v24, v34
	v_mul_f32_e32 v36, v24, v36
	v_mul_f32_e32 v38, v24, v38
	v_mul_f32_e32 v40, v24, v40
	v_mul_f32_e32 v42, v24, v42
	v_mul_f32_e32 v44, v24, v44
	v_mul_f32_e32 v46, v24, v46
	v_mul_f32_e32 v48, v24, v48
	v_mul_f32_e32 v50, v24, v50
	v_mul_f32_e32 v52, v24, v52
	v_mul_f32_e32 v54, v24, v54
	v_mul_f32_e32 v56, v24, v56
	v_mul_f32_e32 v58, v24, v58
	v_mul_f32_e32 v60, v24, v60
	v_mul_f32_e32 v62, v24, v62
	v_mul_f32_e32 v64, v24, v64
	v_mul_f32_e32 v66, v24, v66
	v_mul_f32_e32 v68, v24, v68
	v_mul_f32_e32 v70, v24, v70
	v_mul_f32_e32 v72, v24, v72
	v_mul_f32_e32 v74, v24, v74
	v_mul_f32_e32 v76, v24, v76
	v_mul_f32_e32 v77, v24, v77
	v_mul_f32_e32 v75, v24, v75
	v_mul_f32_e32 v73, v24, v73
	v_mul_f32_e32 v71, v24, v71
	v_mul_f32_e32 v69, v24, v69
	v_mul_f32_e32 v67, v24, v67
	v_mul_f32_e32 v65, v24, v65
	v_mul_f32_e32 v63, v24, v63
	v_mul_f32_e32 v61, v24, v61
	v_mul_f32_e32 v59, v24, v59
	v_mul_f32_e32 v57, v24, v57
	v_mul_f32_e32 v55, v24, v55
	v_mul_f32_e32 v53, v24, v53
	v_mul_f32_e32 v51, v24, v51
	v_mul_f32_e32 v49, v24, v49
	v_mul_f32_e32 v47, v24, v47
	v_mul_f32_e32 v45, v24, v45
	v_mul_f32_e32 v43, v24, v43
	v_mul_f32_e32 v41, v24, v41
	v_mul_f32_e32 v39, v24, v39
	v_mul_f32_e32 v37, v24, v37
	v_mul_f32_e32 v35, v24, v35
	v_mul_f32_e32 v33, v24, v33
	v_mul_f32_e32 v31, v24, v31
	v_mul_f32_e32 v19, v24, v19
	v_mul_f32_e32 v18, v24, v18
	v_mul_f32_e32 v17, v24, v17
	v_mul_f32_e32 v16, v24, v16
	v_mul_f32_e32 v15, v24, v15
	v_mul_f32_e32 v14, v24, v14
	v_mul_f32_e32 v3, v24, v3
	v_mul_f32_e32 v2, v24, v2
	v_mul_f32_e32 v1, v24, v1
	v_mul_f32_e32 v0, v24, v0
	v_mul_f32_e32 v4, v4, v96
	v_mul_f32_e32 v25, v25, v97
	v_mul_f32_e32 v26, v26, v98
	v_mul_f32_e32 v27, v27, v99
	v_mul_f32_e32 v28, v28, v100
	v_mul_f32_e32 v29, v29, v101
	v_mul_f32_e32 v30, v30, v102
	v_mul_f32_e32 v32, v32, v103
	v_mul_f32_e32 v34, v34, v104
	v_mul_f32_e32 v36, v36, v105
	v_mul_f32_e32 v38, v38, v106
	v_mul_f32_e32 v40, v40, v107
	v_mul_f32_e32 v42, v42, v108
	v_mul_f32_e32 v44, v44, v109
	v_mul_f32_e32 v46, v46, v110
	v_mul_f32_e32 v48, v48, v111
	v_mul_f32_e32 v50, v50, v112
	v_mul_f32_e32 v52, v52, v113
	v_mul_f32_e32 v54, v54, v114
	v_mul_f32_e32 v56, v56, v115
	v_mul_f32_e32 v58, v58, v116
	v_mul_f32_e32 v60, v60, v117
	v_mul_f32_e32 v62, v62, v118
	v_mul_f32_e32 v64, v64, v119
	v_mul_f32_e32 v66, v66, v120
	v_mul_f32_e32 v68, v68, v121
	v_mul_f32_e32 v70, v70, v122
	v_mul_f32_e32 v72, v72, v123
	v_mul_f32_e32 v74, v74, v124
	v_mul_f32_e32 v76, v76, v125
	v_mul_f32_e32 v77, v77, v126
	v_mul_f32_e32 v75, v75, v127
	v_mul_f32_e32 v73, v73, v128
	v_mul_f32_e32 v71, v71, v129
	v_mul_f32_e32 v69, v69, v130
	v_mul_f32_e32 v67, v67, v131
	v_mul_f32_e32 v65, v65, v132
	v_mul_f32_e32 v63, v63, v133
	v_mul_f32_e32 v61, v61, v134
	v_mul_f32_e32 v59, v59, v135
	v_mul_f32_e32 v57, v57, v136
	v_mul_f32_e32 v55, v55, v137
	v_mul_f32_e32 v53, v53, v138
	v_mul_f32_e32 v51, v51, v139
	v_mul_f32_e32 v49, v49, v144
	v_mul_f32_e32 v47, v47, v145
	v_mul_f32_e32 v45, v45, v146
	v_mul_f32_e32 v43, v43, v147
	v_mul_f32_e32 v41, v41, v148
	v_mul_f32_e32 v39, v39, v149
	v_mul_f32_e32 v37, v37, v150
	v_mul_f32_e32 v35, v35, v151
	v_mul_f32_e32 v33, v33, v152
	v_mul_f32_e32 v31, v31, v153
	v_mul_f32_e32 v19, v19, v154
	v_mul_f32_e32 v18, v18, v155
	v_mul_f32_e32 v17, v17, v156
	v_mul_f32_e32 v16, v16, v157
	v_mul_f32_e32 v15, v15, v158
	v_mul_f32_e32 v14, v14, v159
	v_mul_f32_e32 v3, v3, v160
	v_mul_f32_e32 v2, v2, v161
	v_mul_f32_e32 v1, v1, v162
	v_mul_f32_e32 v0, v0, v163
	v_mov_b32_dpp v230, v4 quad_perm:[1,0,3,2] row_mask:0xf bank_mask:0xf bound_ctrl:1
	v_mov_b32_dpp v231, v25 quad_perm:[1,0,3,2] row_mask:0xf bank_mask:0xf bound_ctrl:1
	v_mov_b32_dpp v232, v26 quad_perm:[1,0,3,2] row_mask:0xf bank_mask:0xf bound_ctrl:1
	v_mov_b32_dpp v233, v27 quad_perm:[1,0,3,2] row_mask:0xf bank_mask:0xf bound_ctrl:1
	v_mov_b32_dpp v234, v28 quad_perm:[1,0,3,2] row_mask:0xf bank_mask:0xf bound_ctrl:1
	v_mov_b32_dpp v235, v29 quad_perm:[1,0,3,2] row_mask:0xf bank_mask:0xf bound_ctrl:1
	v_mov_b32_dpp v236, v30 quad_perm:[1,0,3,2] row_mask:0xf bank_mask:0xf bound_ctrl:1
	v_mov_b32_dpp v237, v32 quad_perm:[1,0,3,2] row_mask:0xf bank_mask:0xf bound_ctrl:1
	v_mov_b32_dpp v238, v34 quad_perm:[1,0,3,2] row_mask:0xf bank_mask:0xf bound_ctrl:1
	v_mov_b32_dpp v239, v36 quad_perm:[1,0,3,2] row_mask:0xf bank_mask:0xf bound_ctrl:1
	v_mov_b32_dpp v240, v38 quad_perm:[1,0,3,2] row_mask:0xf bank_mask:0xf bound_ctrl:1
	v_mov_b32_dpp v241, v40 quad_perm:[1,0,3,2] row_mask:0xf bank_mask:0xf bound_ctrl:1
	v_mov_b32_dpp v242, v42 quad_perm:[1,0,3,2] row_mask:0xf bank_mask:0xf bound_ctrl:1
	v_mov_b32_dpp v243, v44 quad_perm:[1,0,3,2] row_mask:0xf bank_mask:0xf bound_ctrl:1
	v_mov_b32_dpp v244, v46 quad_perm:[1,0,3,2] row_mask:0xf bank_mask:0xf bound_ctrl:1
	v_mov_b32_dpp v245, v48 quad_perm:[1,0,3,2] row_mask:0xf bank_mask:0xf bound_ctrl:1
	s_waitcnt vmcnt(0)
; template <int CTRL> DI float dpp_f(float x) { return __int_as_float(__builtin_amdgcn_update_dpp(0, __float_as_int(x), CTRL, 0xF, 0xF, true)); }
; template <int HS>
; DI void qknorm_phase(bf16_t* QK, int RL, const float* kgain, int gain_mod, const f32x2* rope) {
;     ...
;         for (int e = 0; e < HS; ++e) {
;             float v = x[e] * r * gn[e];
;             const float o = dpp_f<0xB1>(v);
;             if (lat) { const f32x2 cs = rp[e]; v = half ? (o * cs[1] + v * cs[0]) : (v * cs[0] - o * cs[1]); }
;             x[e] = v;
;         }
	v_mul_f32_e32 v230, v165, v230
	v_mul_f32_e32 v231, v167, v231
	v_mul_f32_e32 v232, v169, v232
	v_mul_f32_e32 v233, v171, v233
	v_mul_f32_e32 v234, v173, v234
	v_mul_f32_e32 v235, v175, v235
	v_mul_f32_e32 v236, v177, v236
	v_mul_f32_e32 v237, v179, v237
	v_mul_f32_e32 v238, v181, v238
	v_mul_f32_e32 v239, v183, v239
	v_mul_f32_e32 v240, v185, v240
	v_mul_f32_e32 v241, v187, v241
	v_mul_f32_e32 v242, v189, v242
	v_mul_f32_e32 v243, v191, v243
	v_mul_f32_e32 v244, v193, v244
	v_mul_f32_e32 v245, v195, v245
	v_cndmask_b32_e64 v230, v230, -v230, vcc
	v_cndmask_b32_e64 v231, v231, -v231, vcc
	v_cndmask_b32_e64 v232, v232, -v232, vcc
	v_cndmask_b32_e64 v233, v233, -v233, vcc
	v_cndmask_b32_e64 v234, v234, -v234, vcc
	v_cndmask_b32_e64 v235, v235, -v235, vcc
	v_cndmask_b32_e64 v236, v236, -v236, vcc
	v_cndmask_b32_e64 v237, v237, -v237, vcc
	v_cndmask_b32_e64 v238, v238, -v238, vcc
	v_cndmask_b32_e64 v239, v239, -v239, vcc
	v_cndmask_b32_e64 v240, v240, -v240, vcc
	v_cndmask_b32_e64 v241, v241, -v241, vcc
	v_cndmask_b32_e64 v242, v242, -v242, vcc
	v_cndmask_b32_e64 v243, v243, -v243, vcc
	v_cndmask_b32_e64 v244, v244, -v244, vcc
	v_cndmask_b32_e64 v245, v245, -v245, vcc
	v_fmac_f32_e32 v230, v4, v164
	v_fmac_f32_e32 v231, v25, v166
	v_fmac_f32_e32 v232, v26, v168
	v_fmac_f32_e32 v233, v27, v170
	v_fmac_f32_e32 v234, v28, v172
	v_fmac_f32_e32 v235, v29, v174
	v_fmac_f32_e32 v236, v30, v176
	v_fmac_f32_e32 v237, v32, v178
	v_fmac_f32_e32 v238, v34, v180
	v_fmac_f32_e32 v239, v36, v182
	v_fmac_f32_e32 v240, v38, v184
	v_fmac_f32_e32 v241, v40, v186
	v_fmac_f32_e32 v242, v42, v188
	v_fmac_f32_e32 v243, v44, v190
	v_fmac_f32_e32 v244, v46, v192
	v_fmac_f32_e32 v245, v48, v194
	v_cndmask_b32_e64 v4, v4, v230, s[4:5]
	v_cndmask_b32_e64 v25, v25, v231, s[4:5]
	v_cndmask_b32_e64 v26, v26, v232, s[4:5]
	v_cndmask_b32_e64 v27, v27, v233, s[4:5]
	v_cndmask_b32_e64 v28, v28, v234, s[4:5]
	v_cndmask_b32_e64 v29, v29, v235, s[4:5]
	v_cndmask_b32_e64 v30, v30, v236, s[4:5]
	v_cndmask_b32_e64 v32, v32, v237, s[4:5]
	v_cndmask_b32_e64 v34, v34, v238, s[4:5]
	v_cndmask_b32_e64 v36, v36, v239, s[4:5]
	v_cndmask_b32_e64 v38, v38, v240, s[4:5]
	v_cndmask_b32_e64 v40, v40, v241, s[4:5]
	v_cndmask_b32_e64 v42, v42, v242, s[4:5]
	v_cndmask_b32_e64 v44, v44, v243, s[4:5]
	v_cndmask_b32_e64 v46, v46, v244, s[4:5]
	v_cndmask_b32_e64 v48, v48, v245, s[4:5]
	v_mov_b32_dpp v230, v50 quad_perm:[1,0,3,2] row_mask:0xf bank_mask:0xf bound_ctrl:1
	v_mov_b32_dpp v231, v52 quad_perm:[1,0,3,2] row_mask:0xf bank_mask:0xf bound_ctrl:1
	v_mov_b32_dpp v232, v54 quad_perm:[1,0,3,2] row_mask:0xf bank_mask:0xf bound_ctrl:1
	v_mov_b32_dpp v233, v56 quad_perm:[1,0,3,2] row_mask:0xf bank_mask:0xf bound_ctrl:1
	v_mov_b32_dpp v234, v58 quad_perm:[1,0,3,2] row_mask:0xf bank_mask:0xf bound_ctrl:1
	v_mov_b32_dpp v235, v60 quad_perm:[1,0,3,2] row_mask:0xf bank_mask:0xf bound_ctrl:1
	v_mov_b32_dpp v236, v62 quad_perm:[1,0,3,2] row_mask:0xf bank_mask:0xf bound_ctrl:1
	v_mov_b32_dpp v237, v64 quad_perm:[1,0,3,2] row_mask:0xf bank_mask:0xf bound_ctrl:1
	v_mov_b32_dpp v238, v66 quad_perm:[1,0,3,2] row_mask:0xf bank_mask:0xf bound_ctrl:1
	v_mov_b32_dpp v239, v68 quad_perm:[1,0,3,2] row_mask:0xf bank_mask:0xf bound_ctrl:1
	v_mov_b32_dpp v240, v70 quad_perm:[1,0,3,2] row_mask:0xf bank_mask:0xf bound_ctrl:1
	v_mov_b32_dpp v241, v72 quad_perm:[1,0,3,2] row_mask:0xf bank_mask:0xf bound_ctrl:1
	v_mov_b32_dpp v242, v74 quad_perm:[1,0,3,2] row_mask:0xf bank_mask:0xf bound_ctrl:1
	v_mov_b32_dpp v243, v76 quad_perm:[1,0,3,2] row_mask:0xf bank_mask:0xf bound_ctrl:1
	v_mov_b32_dpp v244, v77 quad_perm:[1,0,3,2] row_mask:0xf bank_mask:0xf bound_ctrl:1
	v_mov_b32_dpp v245, v75 quad_perm:[1,0,3,2] row_mask:0xf bank_mask:0xf bound_ctrl:1
	v_mul_f32_e32 v230, v197, v230
	v_mul_f32_e32 v231, v199, v231
	v_mul_f32_e32 v232, v201, v232
	v_mul_f32_e32 v233, v203, v233
	v_mul_f32_e32 v234, v205, v234
	v_mul_f32_e32 v235, v207, v235
	v_mul_f32_e32 v236, v209, v236
	v_mul_f32_e32 v237, v211, v237
	v_mul_f32_e32 v238, v213, v238
	v_mul_f32_e32 v239, v215, v239
	v_mul_f32_e32 v240, v217, v240
	v_mul_f32_e32 v241, v219, v241
	v_mul_f32_e32 v242, v221, v242
	v_mul_f32_e32 v243, v223, v243
	v_mul_f32_e32 v244, v225, v244
	v_mul_f32_e32 v245, v227, v245
	v_cndmask_b32_e64 v230, v230, -v230, vcc
	v_cndmask_b32_e64 v231, v231, -v231, vcc
	v_cndmask_b32_e64 v232, v232, -v232, vcc
	v_cndmask_b32_e64 v233, v233, -v233, vcc
	v_cndmask_b32_e64 v234, v234, -v234, vcc
	v_cndmask_b32_e64 v235, v235, -v235, vcc
	v_cndmask_b32_e64 v236, v236, -v236, vcc
	v_cndmask_b32_e64 v237, v237, -v237, vcc
	v_cndmask_b32_e64 v238, v238, -v238, vcc
	v_cndmask_b32_e64 v239, v239, -v239, vcc
	v_cndmask_b32_e64 v240, v240, -v240, vcc
	v_cndmask_b32_e64 v241, v241, -v241, vcc
	v_cndmask_b32_e64 v242, v242, -v242, vcc
	v_cndmask_b32_e64 v243, v243, -v243, vcc
	v_cndmask_b32_e64 v244, v244, -v244, vcc
	v_cndmask_b32_e64 v245, v245, -v245, vcc
	v_fmac_f32_e32 v230, v50, v196
	v_fmac_f32_e32 v231, v52, v198
	v_fmac_f32_e32 v232, v54, v200
	v_fmac_f32_e32 v233, v56, v202
	v_fmac_f32_e32 v234, v58, v204
	v_fmac_f32_e32 v235, v60, v206
	v_fmac_f32_e32 v236, v62, v208
	v_fmac_f32_e32 v237, v64, v210
	v_fmac_f32_e32 v238, v66, v212
	v_fmac_f32_e32 v239, v68, v214
	v_fmac_f32_e32 v240, v70, v216
	v_fmac_f32_e32 v241, v72, v218
	v_fmac_f32_e32 v242, v74, v220
	v_fmac_f32_e32 v243, v76, v222
	v_fmac_f32_e32 v244, v77, v224
	v_fmac_f32_e32 v245, v75, v226
	v_cndmask_b32_e64 v50, v50, v230, s[4:5]
	v_cndmask_b32_e64 v52, v52, v231, s[4:5]
	v_cndmask_b32_e64 v54, v54, v232, s[4:5]
	v_cndmask_b32_e64 v56, v56, v233, s[4:5]
	v_cndmask_b32_e64 v58, v58, v234, s[4:5]
; template <int CTRL> DI float dpp_f(float x) { return __int_as_float(__builtin_amdgcn_update_dpp(0, __float_as_int(x), CTRL, 0xF, 0xF, true)); }
; template <int HS>
; DI void qknorm_phase(bf16_t* QK, int RL, const float* kgain, int gain_mod, const f32x2* rope) {
;     ...
;         for (int e = 0; e < HS; ++e) {
;             float v = x[e] * r * gn[e];
;             const float o = dpp_f<0xB1>(v);
;             if (lat) { const f32x2 cs = rp[e]; v = half ? (o * cs[1] + v * cs[0]) : (v * cs[0] - o * cs[1]); }
;             x[e] = v;
;         }
	v_cndmask_b32_e64 v60, v60, v235, s[4:5]
	v_cndmask_b32_e64 v62, v62, v236, s[4:5]
	v_cndmask_b32_e64 v64, v64, v237, s[4:5]
	v_cndmask_b32_e64 v66, v66, v238, s[4:5]
	v_cndmask_b32_e64 v68, v68, v239, s[4:5]
	v_cndmask_b32_e64 v70, v70, v240, s[4:5]
	v_cndmask_b32_e64 v72, v72, v241, s[4:5]
	v_cndmask_b32_e64 v74, v74, v242, s[4:5]
	v_cndmask_b32_e64 v76, v76, v243, s[4:5]
	v_cndmask_b32_e64 v77, v77, v244, s[4:5]
	v_cndmask_b32_e64 v75, v75, v245, s[4:5]
	global_load_dwordx4 v[164:167], v[228:229], off offset:256
	global_load_dwordx4 v[168:171], v[228:229], off offset:272
	global_load_dwordx4 v[172:175], v[228:229], off offset:288
	global_load_dwordx4 v[176:179], v[228:229], off offset:304
	global_load_dwordx4 v[180:183], v[228:229], off offset:320
	global_load_dwordx4 v[184:187], v[228:229], off offset:336
	global_load_dwordx4 v[188:191], v[228:229], off offset:352
	global_load_dwordx4 v[192:195], v[228:229], off offset:368
	global_load_dwordx4 v[196:199], v[228:229], off offset:384
	global_load_dwordx4 v[200:203], v[228:229], off offset:400
	global_load_dwordx4 v[204:207], v[228:229], off offset:416
	global_load_dwordx4 v[208:211], v[228:229], off offset:432
	global_load_dwordx4 v[212:215], v[228:229], off offset:448
	global_load_dwordx4 v[216:219], v[228:229], off offset:464
	global_load_dwordx4 v[220:223], v[228:229], off offset:480
	global_load_dwordx4 v[224:227], v[228:229], off offset:496
	v_mov_b32_dpp v230, v73 quad_perm:[1,0,3,2] row_mask:0xf bank_mask:0xf bound_ctrl:1
	v_mov_b32_dpp v231, v71 quad_perm:[1,0,3,2] row_mask:0xf bank_mask:0xf bound_ctrl:1
	v_mov_b32_dpp v232, v69 quad_perm:[1,0,3,2] row_mask:0xf bank_mask:0xf bound_ctrl:1
	v_mov_b32_dpp v233, v67 quad_perm:[1,0,3,2] row_mask:0xf bank_mask:0xf bound_ctrl:1
	v_mov_b32_dpp v234, v65 quad_perm:[1,0,3,2] row_mask:0xf bank_mask:0xf bound_ctrl:1
	v_mov_b32_dpp v235, v63 quad_perm:[1,0,3,2] row_mask:0xf bank_mask:0xf bound_ctrl:1
	v_mov_b32_dpp v236, v61 quad_perm:[1,0,3,2] row_mask:0xf bank_mask:0xf bound_ctrl:1
	v_mov_b32_dpp v237, v59 quad_perm:[1,0,3,2] row_mask:0xf bank_mask:0xf bound_ctrl:1
	v_mov_b32_dpp v238, v57 quad_perm:[1,0,3,2] row_mask:0xf bank_mask:0xf bound_ctrl:1
	v_mov_b32_dpp v239, v55 quad_perm:[1,0,3,2] row_mask:0xf bank_mask:0xf bound_ctrl:1
	v_mov_b32_dpp v240, v53 quad_perm:[1,0,3,2] row_mask:0xf bank_mask:0xf bound_ctrl:1
	v_mov_b32_dpp v241, v51 quad_perm:[1,0,3,2] row_mask:0xf bank_mask:0xf bound_ctrl:1
	v_mov_b32_dpp v242, v49 quad_perm:[1,0,3,2] row_mask:0xf bank_mask:0xf bound_ctrl:1
	v_mov_b32_dpp v243, v47 quad_perm:[1,0,3,2] row_mask:0xf bank_mask:0xf bound_ctrl:1
	v_mov_b32_dpp v244, v45 quad_perm:[1,0,3,2] row_mask:0xf bank_mask:0xf bound_ctrl:1
	v_mov_b32_dpp v245, v43 quad_perm:[1,0,3,2] row_mask:0xf bank_mask:0xf bound_ctrl:1
	s_waitcnt vmcnt(0)
	v_mul_f32_e32 v230, v165, v230
	v_mul_f32_e32 v231, v167, v231
	v_mul_f32_e32 v232, v169, v232
	v_mul_f32_e32 v233, v171, v233
	v_mul_f32_e32 v234, v173, v234
	v_mul_f32_e32 v235, v175, v235
	v_mul_f32_e32 v236, v177, v236
	v_mul_f32_e32 v237, v179, v237
	v_mul_f32_e32 v238, v181, v238
	v_mul_f32_e32 v239, v183, v239
	v_mul_f32_e32 v240, v185, v240
	v_mul_f32_e32 v241, v187, v241
	v_mul_f32_e32 v242, v189, v242
	v_mul_f32_e32 v243, v191, v243
	v_mul_f32_e32 v244, v193, v244
	v_mul_f32_e32 v245, v195, v245
	v_cndmask_b32_e64 v230, v230, -v230, vcc
	v_cndmask_b32_e64 v231, v231, -v231, vcc
	v_cndmask_b32_e64 v232, v232, -v232, vcc
	v_cndmask_b32_e64 v233, v233, -v233, vcc
	v_cndmask_b32_e64 v234, v234, -v234, vcc
	v_cndmask_b32_e64 v235, v235, -v235, vcc
	v_cndmask_b32_e64 v236, v236, -v236, vcc
	v_cndmask_b32_e64 v237, v237, -v237, vcc
	v_cndmask_b32_e64 v238, v238, -v238, vcc
	v_cndmask_b32_e64 v239, v239, -v239, vcc
	v_cndmask_b32_e64 v240, v240, -v240, vcc
	v_cndmask_b32_e64 v241, v241, -v241, vcc
	v_cndmask_b32_e64 v242, v242, -v242, vcc
	v_cndmask_b32_e64 v243, v243, -v243, vcc
	v_cndmask_b32_e64 v244, v244, -v244, vcc
	v_cndmask_b32_e64 v245, v245, -v245, vcc
	v_fmac_f32_e32 v230, v73, v164
	v_fmac_f32_e32 v231, v71, v166
	v_fmac_f32_e32 v232, v69, v168
	v_fmac_f32_e32 v233, v67, v170
	v_fmac_f32_e32 v234, v65, v172
	v_fmac_f32_e32 v235, v63, v174
	v_fmac_f32_e32 v236, v61, v176
	v_fmac_f32_e32 v237, v59, v178
	v_fmac_f32_e32 v238, v57, v180
	v_fmac_f32_e32 v239, v55, v182
	v_fmac_f32_e32 v240, v53, v184
	v_fmac_f32_e32 v241, v51, v186
	v_fmac_f32_e32 v242, v49, v188
	v_fmac_f32_e32 v243, v47, v190
	v_fmac_f32_e32 v244, v45, v192
	v_fmac_f32_e32 v245, v43, v194
	v_cndmask_b32_e64 v73, v73, v230, s[4:5]
	v_cndmask_b32_e64 v71, v71, v231, s[4:5]
	v_cndmask_b32_e64 v69, v69, v232, s[4:5]
	v_cndmask_b32_e64 v67, v67, v233, s[4:5]
	v_cndmask_b32_e64 v65, v65, v234, s[4:5]
	v_cndmask_b32_e64 v63, v63, v235, s[4:5]
	v_cndmask_b32_e64 v61, v61, v236, s[4:5]
	v_cndmask_b32_e64 v59, v59, v237, s[4:5]
	v_cndmask_b32_e64 v57, v57, v238, s[4:5]
	v_cndmask_b32_e64 v55, v55, v239, s[4:5]
	v_cndmask_b32_e64 v53, v53, v240, s[4:5]
	v_cndmask_b32_e64 v51, v51, v241, s[4:5]
	v_cndmask_b32_e64 v49, v49, v242, s[4:5]
	v_cndmask_b32_e64 v47, v47, v243, s[4:5]
	v_cndmask_b32_e64 v45, v45, v244, s[4:5]
	v_cndmask_b32_e64 v43, v43, v245, s[4:5]
	v_mov_b32_dpp v230, v41 quad_perm:[1,0,3,2] row_mask:0xf bank_mask:0xf bound_ctrl:1
; DI unsigned pack2(float lo, float hi) { const f32x2 v = (f32x2){lo, hi}; return __builtin_bit_cast(unsigned, __builtin_convertvector(v, bf16x2_t)); }
; template <int CTRL> DI float dpp_f(float x) { return __int_as_float(__builtin_amdgcn_update_dpp(0, __float_as_int(x), CTRL, 0xF, 0xF, true)); }
; template <int HS>
; DI void qknorm_phase(bf16_t* QK, int RL, const float* kgain, int gain_mod, const f32x2* rope) {
;     ...
;         for (int e = 0; e < HS; ++e) {
;             float v = x[e] * r * gn[e];
;             const float o = dpp_f<0xB1>(v);
;             if (lat) { const f32x2 cs = rp[e]; v = half ? (o * cs[1] + v * cs[0]) : (v * cs[0] - o * cs[1]); }
;             x[e] = v;
;         }
;         if (act) {
; #pragma unroll
;             for (int c = 0; c < HS / 8; ++c) { u32x4 w; w.x = pack2(x[c * 8], x[c * 8 + 1]); w.y = pack2(x[c * 8 + 2], x[c * 8 + 3]); w.z = pack2(x[c * 8 + 4], x[c * 8 + 5]); w.w = pack2(x[c * 8 + 6], x[c * 8 + 7]);
;                 *(u32x4*)(ptr + c * 8) = w; }
;         }
	v_mov_b32_dpp v231, v39 quad_perm:[1,0,3,2] row_mask:0xf bank_mask:0xf bound_ctrl:1
	v_mov_b32_dpp v232, v37 quad_perm:[1,0,3,2] row_mask:0xf bank_mask:0xf bound_ctrl:1
	v_mov_b32_dpp v233, v35 quad_perm:[1,0,3,2] row_mask:0xf bank_mask:0xf bound_ctrl:1
	v_mov_b32_dpp v234, v33 quad_perm:[1,0,3,2] row_mask:0xf bank_mask:0xf bound_ctrl:1
	v_mov_b32_dpp v235, v31 quad_perm:[1,0,3,2] row_mask:0xf bank_mask:0xf bound_ctrl:1
	v_mov_b32_dpp v236, v19 quad_perm:[1,0,3,2] row_mask:0xf bank_mask:0xf bound_ctrl:1
	v_mov_b32_dpp v237, v18 quad_perm:[1,0,3,2] row_mask:0xf bank_mask:0xf bound_ctrl:1
	v_mov_b32_dpp v238, v17 quad_perm:[1,0,3,2] row_mask:0xf bank_mask:0xf bound_ctrl:1
	v_mov_b32_dpp v239, v16 quad_perm:[1,0,3,2] row_mask:0xf bank_mask:0xf bound_ctrl:1
	v_mov_b32_dpp v240, v15 quad_perm:[1,0,3,2] row_mask:0xf bank_mask:0xf bound_ctrl:1
	v_mov_b32_dpp v241, v14 quad_perm:[1,0,3,2] row_mask:0xf bank_mask:0xf bound_ctrl:1
	v_mov_b32_dpp v242, v3 quad_perm:[1,0,3,2] row_mask:0xf bank_mask:0xf bound_ctrl:1
	v_mov_b32_dpp v243, v2 quad_perm:[1,0,3,2] row_mask:0xf bank_mask:0xf bound_ctrl:1
	v_mov_b32_dpp v244, v1 quad_perm:[1,0,3,2] row_mask:0xf bank_mask:0xf bound_ctrl:1
	v_mov_b32_dpp v245, v0 quad_perm:[1,0,3,2] row_mask:0xf bank_mask:0xf bound_ctrl:1
	v_mul_f32_e32 v230, v197, v230
	v_mul_f32_e32 v231, v199, v231
	v_mul_f32_e32 v232, v201, v232
	v_mul_f32_e32 v233, v203, v233
	v_mul_f32_e32 v234, v205, v234
	v_mul_f32_e32 v235, v207, v235
	v_mul_f32_e32 v236, v209, v236
	v_mul_f32_e32 v237, v211, v237
	v_mul_f32_e32 v238, v213, v238
	v_mul_f32_e32 v239, v215, v239
	v_mul_f32_e32 v240, v217, v240
	v_mul_f32_e32 v241, v219, v241
	v_mul_f32_e32 v242, v221, v242
	v_mul_f32_e32 v243, v223, v243
	v_mul_f32_e32 v244, v225, v244
	v_mul_f32_e32 v245, v227, v245
	v_cndmask_b32_e64 v230, v230, -v230, vcc
	v_cndmask_b32_e64 v231, v231, -v231, vcc
	v_cndmask_b32_e64 v232, v232, -v232, vcc
	v_cndmask_b32_e64 v233, v233, -v233, vcc
	v_cndmask_b32_e64 v234, v234, -v234, vcc
	v_cndmask_b32_e64 v235, v235, -v235, vcc
	v_cndmask_b32_e64 v236, v236, -v236, vcc
	v_cndmask_b32_e64 v237, v237, -v237, vcc
	v_cndmask_b32_e64 v238, v238, -v238, vcc
	v_cndmask_b32_e64 v239, v239, -v239, vcc
	v_cndmask_b32_e64 v240, v240, -v240, vcc
	v_cndmask_b32_e64 v241, v241, -v241, vcc
	v_cndmask_b32_e64 v242, v242, -v242, vcc
	v_cndmask_b32_e64 v243, v243, -v243, vcc
	v_cndmask_b32_e64 v244, v244, -v244, vcc
	v_cndmask_b32_e64 v245, v245, -v245, vcc
	v_fmac_f32_e32 v230, v41, v196
	v_fmac_f32_e32 v231, v39, v198
	v_fmac_f32_e32 v232, v37, v200
	v_fmac_f32_e32 v233, v35, v202
	v_fmac_f32_e32 v234, v33, v204
	v_fmac_f32_e32 v235, v31, v206
	v_fmac_f32_e32 v236, v19, v208
	v_fmac_f32_e32 v237, v18, v210
	v_fmac_f32_e32 v238, v17, v212
	v_fmac_f32_e32 v239, v16, v214
	v_fmac_f32_e32 v240, v15, v216
	v_fmac_f32_e32 v241, v14, v218
	v_fmac_f32_e32 v242, v3, v220
	v_fmac_f32_e32 v243, v2, v222
	v_fmac_f32_e32 v244, v1, v224
	v_fmac_f32_e32 v245, v0, v226
	v_cndmask_b32_e64 v41, v41, v230, s[4:5]
	v_cndmask_b32_e64 v39, v39, v231, s[4:5]
	v_cndmask_b32_e64 v37, v37, v232, s[4:5]
	v_cndmask_b32_e64 v35, v35, v233, s[4:5]
	v_cndmask_b32_e64 v33, v33, v234, s[4:5]
	v_cndmask_b32_e64 v31, v31, v235, s[4:5]
	v_cndmask_b32_e64 v19, v19, v236, s[4:5]
	v_cndmask_b32_e64 v18, v18, v237, s[4:5]
	v_cndmask_b32_e64 v17, v17, v238, s[4:5]
	v_cndmask_b32_e64 v16, v16, v239, s[4:5]
	v_cndmask_b32_e64 v15, v15, v240, s[4:5]
	v_cndmask_b32_e64 v14, v14, v241, s[4:5]
	v_cndmask_b32_e64 v3, v3, v242, s[4:5]
	v_cndmask_b32_e64 v2, v2, v243, s[4:5]
	v_cndmask_b32_e64 v1, v1, v244, s[4:5]
	v_cndmask_b32_e64 v0, v0, v245, s[4:5]
	s_and_saveexec_b64 s[0:1], s[2:3]
	s_cbranch_execz .LBB0_3204
	v_cvt_pk_bf16_f32 v24, v4, v25
	v_cvt_pk_bf16_f32 v25, v26, v27
	v_cvt_pk_bf16_f32 v26, v28, v29
	v_cvt_pk_bf16_f32 v27, v30, v32
	global_store_dwordx4 v[10:11], v[24:27], off offset:2048
	v_cvt_pk_bf16_f32 v12, v17, v16
	v_cvt_pk_bf16_f32 v13, v15, v14
	v_cvt_pk_bf16_f32 v24, v34, v36
	v_cvt_pk_bf16_f32 v25, v38, v40
	v_cvt_pk_bf16_f32 v26, v42, v44
	v_cvt_pk_bf16_f32 v27, v46, v48
	global_store_dwordx4 v[10:11], v[24:27], off offset:2064
	v_cvt_pk_bf16_f32 v14, v3, v2
	v_cvt_pk_bf16_f32 v15, v1, v0
	v_cvt_pk_bf16_f32 v24, v50, v52
	v_cvt_pk_bf16_f32 v25, v54, v56
	v_cvt_pk_bf16_f32 v26, v58, v60
	v_cvt_pk_bf16_f32 v27, v62, v64
	global_store_dwordx4 v[10:11], v[24:27], off offset:2080
	global_store_dwordx4 v[10:11], v[12:15], off offset:2160
	s_nop 0
	v_cvt_pk_bf16_f32 v24, v66, v68
	v_cvt_pk_bf16_f32 v25, v70, v72
	v_cvt_pk_bf16_f32 v26, v74, v76
	v_cvt_pk_bf16_f32 v27, v77, v75
	global_store_dwordx4 v[10:11], v[24:27], off offset:2096
	s_nop 1
	v_cvt_pk_bf16_f32 v24, v73, v71
	v_cvt_pk_bf16_f32 v25, v69, v67
	v_cvt_pk_bf16_f32 v26, v65, v63
	v_cvt_pk_bf16_f32 v27, v61, v59
	global_store_dwordx4 v[10:11], v[24:27], off offset:2112
	s_nop 1
	v_cvt_pk_bf16_f32 v24, v57, v55
	v_cvt_pk_bf16_f32 v25, v53, v51
	v_cvt_pk_bf16_f32 v26, v49, v47
	v_cvt_pk_bf16_f32 v27, v45, v43
	global_store_dwordx4 v[10:11], v[24:27], off offset:2128
	s_nop 1
	v_cvt_pk_bf16_f32 v24, v41, v39
	v_cvt_pk_bf16_f32 v25, v37, v35
	v_cvt_pk_bf16_f32 v26, v33, v31
	v_cvt_pk_bf16_f32 v27, v19, v18
	global_store_dwordx4 v[10:11], v[24:27], off offset:2144
	s_branch .LBB0_3204
